# first seam hand-written too (census + panel/XCD check inside it); panel-local seams only before Q-proj, Wo and FFN2 gate-up
# speedup vs baseline: 1.0077x; 1.0077x over previous
; #define SEAM(k) do { if (IN(k) && IN((k) + 1)) flat_barrier((unsigned*)(ws + WS_BAR + 65536), fgen, (unsigned)G); } while (0)
; #define SEAM(k) do { if (IN(k) && IN((k) + 1)) xcd_barrier(xbar); } while (0)
; __device__ __forceinline__ void panel_sync(unsigned* cnt, int pm, int wid, int lane) {
;     asm volatile("s_waitcnt vmcnt(0) lgkmcnt(0)" ::: "memory"); __builtin_amdgcn_s_barrier(); asm volatile("" ::: "memory");
;     if (wid == 0) {
;         if (lane == 0) { __builtin_amdgcn_fence(__ATOMIC_RELEASE, "agent"); asm volatile("s_waitcnt vmcnt(0)" ::: "memory"); __hip_atomic_fetch_add(cnt + 64 * pm, 1u, __ATOMIC_RELAXED, __HIP_MEMORY_SCOPE_AGENT); }
;         unsigned sp = 0;
;         while ((unsigned)__builtin_amdgcn_readfirstlane(__hip_atomic_load(cnt + 64 * pm, __ATOMIC_RELAXED, __HIP_MEMORY_SCOPE_AGENT)) < 4u) { __builtin_amdgcn_s_sleep(2); if (++sp > (1u << 22)) break; }
;         __builtin_amdgcn_fence(__ATOMIC_ACQUIRE, "agent");
;         asm volatile("s_waitcnt vmcnt(0)" ::: "memory");
;     }
;     asm volatile("" ::: "memory"); __builtin_amdgcn_s_barrier(); asm volatile("" ::: "memory");
; __global__ void __launch_bounds__(NT, 2) hymba_fwd(Args args) {
;     ...
;     SEAM(7);
.LBB0_1035:
	s_cmp_gt_i32 s51, 8
	s_cselect_b64 s[4:5], -1, 0
	s_and_b64 s[6:7], s[8:9], s[4:5]
	s_andn2_b64 vcc, exec, s[6:7]
	s_cbranch_vccnz .LBB0_1089
	v_mov_b32_e32 v1, 0x23fc8
	ds_read_b32 v2, v1
	s_waitcnt lgkmcnt(0)
	v_readfirstlane_b32 s14, v2
	s_cmp_lg_u32 s14, 1
	s_cbranch_scc1 .Lgb6_full
	s_waitcnt vmcnt(0)
	s_barrier
	s_cmp_eq_u64 s[44:45], 0
	s_cbranch_scc1 .Lgb6_gend
	s_mov_b64 s[8:9], exec
	s_mov_b64 exec, s[44:45]
	v_mov_b32_e32 v1, 1
	s_and_b32 s10, s2, 63
	s_lshl_b32 s10, s10, 8
	s_add_u32 s12, s46, s10
	s_addc_u32 s13, s47, 0
	v_mov_b32_e32 v0, 0xc000
	global_atomic_add v0, v1, s[12:13]
	s_mov_b32 s19, 0
.Lgb6_gpoll:
	global_load_dword v4, v0, s[12:13] sc1
	s_waitcnt vmcnt(0)
	v_readfirstlane_b32 s14, v4
	s_cmp_ge_u32 s14, 4
	s_cbranch_scc1 .Lgb6_gpanel
	s_sleep 1
	s_add_i32 s19, s19, 1
	s_cmp_lt_u32 s19, 20000
	s_cbranch_scc1 .Lgb6_gpoll
.Lgb6_gpanel:
.Lgb6_gacq:
	buffer_inv sc1
	s_waitcnt vmcnt(0)
	s_mov_b64 exec, s[8:9]

; #define SEAM(k) do { if (IN(k) && IN((k) + 1)) flat_barrier((unsigned*)(ws + WS_BAR + 65536), fgen, (unsigned)G); } while (0)
; #define SEAM(k) do { if (IN(k) && IN((k) + 1)) xcd_barrier(xbar); } while (0)
; __device__ __forceinline__ void panel_sync(unsigned* cnt, int pm, int wid, int lane) {
;     asm volatile("s_waitcnt vmcnt(0) lgkmcnt(0)" ::: "memory"); __builtin_amdgcn_s_barrier(); asm volatile("" ::: "memory");
;     if (wid == 0) {
;         if (lane == 0) { __builtin_amdgcn_fence(__ATOMIC_RELEASE, "agent"); asm volatile("s_waitcnt vmcnt(0)" ::: "memory"); __hip_atomic_fetch_add(cnt + 64 * pm, 1u, __ATOMIC_RELAXED, __HIP_MEMORY_SCOPE_AGENT); }
;         unsigned sp = 0;
;         while ((unsigned)__builtin_amdgcn_readfirstlane(__hip_atomic_load(cnt + 64 * pm, __ATOMIC_RELAXED, __HIP_MEMORY_SCOPE_AGENT)) < 4u) { __builtin_amdgcn_s_sleep(2); if (++sp > (1u << 22)) break; }
;         __builtin_amdgcn_fence(__ATOMIC_ACQUIRE, "agent");
;         asm volatile("s_waitcnt vmcnt(0)" ::: "memory");
;     }
;     asm volatile("" ::: "memory"); __builtin_amdgcn_s_barrier(); asm volatile("" ::: "memory");
; __global__ void __launch_bounds__(NT, 2) hymba_fwd(Args args) {
;     ...
;     SEAM(8);
.LBB0_1111:
	s_cmp_gt_u32 s51, 9
	s_cselect_b64 s[4:5], -1, 0
	s_and_b64 s[4:5], s[8:9], s[4:5]
	s_andn2_b64 vcc, exec, s[4:5]
	s_cbranch_vccnz .LBB0_1165
	v_mov_b32_e32 v1, 0x23fc8
	ds_read_b32 v2, v1
	s_waitcnt lgkmcnt(0)
	v_readfirstlane_b32 s14, v2
	s_cmp_lg_u32 s14, 1
	s_cbranch_scc1 .Lgb7_full
	s_waitcnt vmcnt(0)
	s_barrier
	s_cmp_eq_u64 s[44:45], 0
	s_cbranch_scc1 .Lgb7_gend
	s_mov_b64 s[8:9], exec
	s_mov_b64 exec, s[44:45]
	v_mov_b32_e32 v1, 1
	s_and_b32 s10, s2, 63
	s_lshl_b32 s10, s10, 8
	s_add_u32 s12, s46, s10
	s_addc_u32 s13, s47, 0
	v_mov_b32_e32 v0, 0xc000
	global_atomic_add v0, v1, s[12:13]
	s_mov_b32 s19, 0
.Lgb7_gpoll:
	global_load_dword v4, v0, s[12:13] sc1
	s_waitcnt vmcnt(0)
	v_readfirstlane_b32 s14, v4
	s_cmp_ge_u32 s14, 8
	s_cbranch_scc1 .Lgb7_gpanel
	s_sleep 1
	s_add_i32 s19, s19, 1
	s_cmp_lt_u32 s19, 20000
	s_cbranch_scc1 .Lgb7_gpoll

; #define SEAM(k) do { if (IN(k) && IN((k) + 1)) flat_barrier((unsigned*)(ws + WS_BAR + 65536), fgen, (unsigned)G); } while (0)
; #define SEAM(k) do { if (IN(k) && IN((k) + 1)) xcd_barrier(xbar); } while (0)
; __device__ __forceinline__ void panel_sync(unsigned* cnt, int pm, int wid, int lane) {
;     asm volatile("s_waitcnt vmcnt(0) lgkmcnt(0)" ::: "memory"); __builtin_amdgcn_s_barrier(); asm volatile("" ::: "memory");
;     if (wid == 0) {
;         if (lane == 0) { __builtin_amdgcn_fence(__ATOMIC_RELEASE, "agent"); asm volatile("s_waitcnt vmcnt(0)" ::: "memory"); __hip_atomic_fetch_add(cnt + 64 * pm, 1u, __ATOMIC_RELAXED, __HIP_MEMORY_SCOPE_AGENT); }
;         unsigned sp = 0;
;         while ((unsigned)__builtin_amdgcn_readfirstlane(__hip_atomic_load(cnt + 64 * pm, __ATOMIC_RELAXED, __HIP_MEMORY_SCOPE_AGENT)) < 4u) { __builtin_amdgcn_s_sleep(2); if (++sp > (1u << 22)) break; }
;         __builtin_amdgcn_fence(__ATOMIC_ACQUIRE, "agent");
;         asm volatile("s_waitcnt vmcnt(0)" ::: "memory");
;     }
;     asm volatile("" ::: "memory"); __builtin_amdgcn_s_barrier(); asm volatile("" ::: "memory");
; __global__ void __launch_bounds__(NT, 2) hymba_fwd(Args args) {
;     ...
;     SEAM(10);
.LBB0_1207:
	s_cmp_gt_i32 s51, 11
	s_cselect_b64 s[4:5], -1, 0
	s_and_b64 s[6:7], s[8:9], s[4:5]
	s_andn2_b64 vcc, exec, s[6:7]
	s_cbranch_vccnz .LBB0_1261
	v_mov_b32_e32 v1, 0x23fc8
	ds_read_b32 v2, v1
	s_waitcnt lgkmcnt(0)
	v_readfirstlane_b32 s14, v2
	s_cmp_lg_u32 s14, 1
	s_cbranch_scc1 .Lgb8_full
	s_waitcnt vmcnt(0)
	s_barrier
	s_cmp_eq_u64 s[44:45], 0
	s_cbranch_scc1 .Lgb8_gend
	s_mov_b64 s[8:9], exec
	s_mov_b64 exec, s[44:45]
	v_mov_b32_e32 v1, 1
	s_and_b32 s10, s2, 63
	s_lshl_b32 s10, s10, 8
	s_add_u32 s12, s46, s10
	s_addc_u32 s13, s47, 0
	v_mov_b32_e32 v0, 0xc000
	global_atomic_add v0, v1, s[12:13]
	s_mov_b32 s19, 0
.Lgb8_gpoll:
	global_load_dword v4, v0, s[12:13] sc1
	s_waitcnt vmcnt(0)
	v_readfirstlane_b32 s14, v4
	s_cmp_ge_u32 s14, 12
	s_cbranch_scc1 .Lgb8_gpanel
	s_sleep 1
	s_add_i32 s19, s19, 1
	s_cmp_lt_u32 s19, 20000
	s_cbranch_scc1 .Lgb8_gpoll
